# v19 + dilated attention tile ring deepened from 4 to 8 stages (7 key/value tiles in flight per CU instead of 3; LDS has the room)
# baseline (speedup 1.0000x reference)
.LBB0_398:
	s_and_b64 vcc, exec, s[0:1]
	s_cbranch_vccz .LBB0_375
	s_ashr_i32 s90, s78, 9
	s_lshl_b32 s0, s90, 1
	s_lshl_b32 s4, s78, 8
	s_lshr_b32 s1, 0x1000, s0
	s_and_b32 s4, s4, 0xf00
	s_sub_i32 s0, 12, s0
	s_lshr_b32 s0, s4, s0
	s_mul_i32 s1, s0, s1
	s_sub_i32 s0, s4, s1
	s_ashr_i32 s91, s90, 31
	s_lshl_b32 s4, s78, 5
	s_ashr_i32 s86, s0, 5
	v_readlane_b32 s0, v254, 16
	s_lshl_b64 s[90:91], s[90:91], 14
	s_and_b32 s4, s4, 0x3000
	s_bfe_u32 s79, s78, 0x30004
	s_add_i32 s87, s86, s0
	s_max_i32 s0, s86, 4
	s_or_b32 s4, s90, s4
	s_add_u32 s90, s4, s1
	s_addc_u32 s91, s91, 0
	v_lshl_or_b32 v132, s87, 5, v165
	s_lshl_b64 vcc, s[90:91], 11
	v_readlane_b32 s1, v254, 30
	v_ashrrev_i32_e32 v133, 31, v132
	s_add_u32 s1, s1, vcc_lo
	v_readlane_b32 s4, v254, 31
	v_lshl_add_u64 v[130:131], s[90:91], 0, v[132:133]
	s_addc_u32 s4, s4, vcc_hi
	s_lshl_b32 s76, s79, 8
	s_add_i32 s46, s86, 7
	s_add_i32 s90, s0, -4
	v_readlane_b32 s66, v254, 35
	s_add_u32 s66, s66, vcc_lo
	v_readlane_b32 s67, v254, 34
	s_addc_u32 s67, s67, vcc_hi
	v_lshlrev_b64 v[4:5], 11, v[130:131]
	s_add_u32 vcc_lo, s66, s76
	v_lshl_add_u64 v[4:5], s[70:71], 0, v[4:5]
	s_addc_u32 vcc_hi, s67, 0
	v_lshl_add_u64 v[4:5], v[4:5], 0, s[76:77]
	v_mov_b32_e32 v173, v3
	s_add_u32 s66, s1, s76
	v_lshl_add_u64 v[4:5], v[4:5], 0, v[172:173]
	s_addc_u32 s67, s4, 0
	s_max_i32 s1, s46, s90
	global_load_dwordx4 v[98:101], v[4:5], off
	global_load_dwordx4 v[102:105], v[4:5], off offset:32
	global_load_dwordx4 v[106:109], v[4:5], off offset:64
	global_load_dwordx4 v[110:113], v[4:5], off offset:96
	global_load_dwordx4 v[114:117], v[4:5], off offset:128
	global_load_dwordx4 v[118:121], v[4:5], off offset:160
	global_load_dwordx4 v[122:125], v[4:5], off offset:192
	global_load_dwordx4 v[126:129], v[4:5], off offset:224
	v_lshl_add_u64 v[4:5], vcc, 0, v[170:171]
	v_lshlrev_b32_e32 v2, 1, v164
	s_lshl_b32 s76, s1, 5
	s_add_i32 s1, s86, 6
	v_lshl_add_u64 v[134:135], v[4:5], 0, v[2:3]
	v_lshl_add_u64 v[4:5], s[66:67], 0, v[170:171]
	s_lshl_b64 s[66:67], s[76:77], 11
	s_max_i32 s1, s1, s90
	s_mov_b32 m0, s94
	v_lshl_add_u64 v[136:137], v[4:5], 0, v[2:3]
	v_lshl_add_u64 v[4:5], v[134:135], 0, s[66:67]
	s_lshl_b32 s76, s1, 5
	s_add_i32 s1, s86, 5
	global_load_lds_dwordx4 v[4:5], off
	v_lshl_add_u64 v[4:5], v[136:137], 0, s[66:67]
	s_mov_b32 m0, s56
	s_lshl_b64 s[66:67], s[76:77], 11
	s_max_i32 s1, s1, s90
	global_load_lds_dwordx4 v[4:5], off
	v_lshl_add_u64 v[4:5], v[134:135], 0, s[66:67]
	s_mov_b32 m0, s57
	s_lshl_b32 s76, s1, 5
	global_load_lds_dwordx4 v[4:5], off
	v_lshl_add_u64 v[4:5], v[136:137], 0, s[66:67]
	s_mov_b32 m0, s89
	s_lshl_b64 s[66:67], s[76:77], 11
	global_load_lds_dwordx4 v[4:5], off
	v_lshl_add_u64 v[4:5], v[134:135], 0, s[66:67]
	s_mov_b32 m0, s93
	s_nop 0
	global_load_lds_dwordx4 v[4:5], off
	v_lshl_add_u64 v[4:5], v[136:137], 0, s[66:67]
	s_mov_b32 m0, s68
	s_nop 0
	global_load_lds_dwordx4 v[4:5], off
	s_add_i32 s1, s86, 4
	s_max_i32 s1, s1, s90
	s_lshl_b32 s76, s1, 5
	s_lshl_b64 s[66:67], s[76:77], 11
	v_lshl_add_u64 v[4:5], v[134:135], 0, s[66:67]
	s_add_i32 m0, s94, 0xc000
	s_nop 0
	global_load_lds_dwordx4 v[4:5], off
	v_lshl_add_u64 v[4:5], v[136:137], 0, s[66:67]
	s_add_i32 m0, s94, 0xe000
	s_nop 0
	global_load_lds_dwordx4 v[4:5], off
	s_add_i32 s1, s86, 3
	s_max_i32 s1, s1, s90
	s_lshl_b32 s76, s1, 5
	s_lshl_b64 s[66:67], s[76:77], 11
	v_lshl_add_u64 v[4:5], v[134:135], 0, s[66:67]
	s_add_i32 m0, s94, 0x10000
	s_nop 0
	global_load_lds_dwordx4 v[4:5], off
	v_lshl_add_u64 v[4:5], v[136:137], 0, s[66:67]
	s_add_i32 m0, s94, 0x12000
	s_nop 0
	global_load_lds_dwordx4 v[4:5], off
	s_add_i32 s1, s86, 2
	s_max_i32 s1, s1, s90
	s_lshl_b32 s76, s1, 5
	s_lshl_b64 s[66:67], s[76:77], 11
	v_lshl_add_u64 v[4:5], v[134:135], 0, s[66:67]
	s_add_i32 m0, s94, 0x14000
	s_nop 0
	global_load_lds_dwordx4 v[4:5], off
	v_lshl_add_u64 v[4:5], v[136:137], 0, s[66:67]
	s_add_i32 m0, s94, 0x16000
	s_nop 0
	global_load_lds_dwordx4 v[4:5], off
	s_add_i32 s1, s86, 1
	s_max_i32 s1, s1, s90
	s_lshl_b32 s76, s1, 5
	s_lshl_b64 s[66:67], s[76:77], 11
	v_lshl_add_u64 v[4:5], v[134:135], 0, s[66:67]
	s_add_i32 m0, s94, 0x18000
	s_nop 0
	global_load_lds_dwordx4 v[4:5], off
	v_lshl_add_u64 v[4:5], v[136:137], 0, s[66:67]
	s_add_i32 m0, s94, 0x1a000
	s_nop 0
	global_load_lds_dwordx4 v[4:5], off
	s_cmp_lt_i32 s46, s90
	s_cbranch_scc1 .LBB0_411
	v_mov_b32_e32 v16, v3
	v_mov_b32_e32 v17, v3
	s_sub_i32 s91, s0, s86
	v_mov_b32_e32 v2, v3
	v_mov_b32_e32 v4, v3
	v_mov_b32_e32 v5, v3
	v_mov_b32_e32 v6, v3
	v_mov_b32_e32 v7, v3
	v_mov_b32_e32 v8, v3
	v_mov_b32_e32 v9, v3
	v_mov_b32_e32 v10, v3
	v_mov_b32_e32 v11, v3
	v_mov_b32_e32 v12, v3
	v_mov_b32_e32 v13, v3
	v_mov_b32_e32 v14, v3
	v_mov_b32_e32 v15, v3
	v_mov_b64_e32 v[32:33], v[16:17]
	v_mov_b64_e32 v[48:49], v[16:17]
	v_mov_b64_e32 v[64:65], v[16:17]
	v_mov_b64_e32 v[80:81], v[16:17]
	s_add_i32 s91, s91, -12
	v_lshl_add_u32 v1, s86, 5, v198
	s_mov_b32 s69, 0
	v_mov_b32_e32 v133, 0
	v_mov_b32_e32 v138, 0xf149f2ca
	s_mov_b32 s4, 0
	v_mov_b64_e32 v[30:31], v[14:15]
	v_mov_b64_e32 v[28:29], v[12:13]
	v_mov_b64_e32 v[26:27], v[10:11]
	v_mov_b64_e32 v[24:25], v[8:9]
	v_mov_b64_e32 v[22:23], v[6:7]
	v_mov_b64_e32 v[20:21], v[4:5]
	v_mov_b64_e32 v[18:19], v[2:3]
	v_mov_b64_e32 v[46:47], v[14:15]
	v_mov_b64_e32 v[44:45], v[12:13]
	v_mov_b64_e32 v[42:43], v[10:11]
	v_mov_b64_e32 v[40:41], v[8:9]
	v_mov_b64_e32 v[38:39], v[6:7]
	v_mov_b64_e32 v[36:37], v[4:5]
	v_mov_b64_e32 v[34:35], v[2:3]
	v_mov_b64_e32 v[62:63], v[14:15]
	v_mov_b64_e32 v[60:61], v[12:13]
	v_mov_b64_e32 v[58:59], v[10:11]
	v_mov_b64_e32 v[56:57], v[8:9]
	v_mov_b64_e32 v[54:55], v[6:7]
	v_mov_b64_e32 v[52:53], v[4:5]
	v_mov_b64_e32 v[50:51], v[2:3]
	v_mov_b64_e32 v[78:79], v[14:15]
	v_mov_b64_e32 v[76:77], v[12:13]
	v_mov_b64_e32 v[74:75], v[10:11]
	v_mov_b64_e32 v[72:73], v[8:9]
	v_mov_b64_e32 v[70:71], v[6:7]
	v_mov_b64_e32 v[68:69], v[4:5]
	v_mov_b64_e32 v[66:67], v[2:3]
	s_branch .LBB0_403

.LBB0_403:
	s_add_i32 s0, s86, s4
	s_add_i32 s1, s0, 0
	s_max_i32 s1, s1, s90
	s_add_i32 s46, s69, 0x1c000
	s_and_b32 s46, s46, 0x1c000
	s_lshl_b32 s76, s1, 5
	s_waitcnt vmcnt(12)
	s_lshl_b64 s[66:67], s[76:77], 11
	s_add_i32 s1, s94, s46
	s_waitcnt lgkmcnt(0)
	s_barrier
	v_lshl_add_u64 v[4:5], v[134:135], 0, s[66:67]
	s_mov_b32 m0, s1
	s_nop 0
	global_load_lds_dwordx4 v[4:5], off
	v_lshl_add_u64 v[4:5], v[136:137], 0, s[66:67]
	s_add_i32 m0, s1, 0x2000
	s_add_i32 s1, s0, 7
	global_load_lds_dwordx4 v[4:5], off
	s_cmp_gt_i32 s1, s87
	s_cbranch_scc1 .LBB0_402
	s_add_i32 s0, s0, 11
	s_cmp_lt_i32 s0, s87
	s_cbranch_scc1 .LBB0_402
	s_and_b32 s0, s69, 0x1c000
	s_add_i32 s46, s0, 0
	v_add_u32_e32 v2, s46, v181
	v_add_u32_e32 v4, v2, v183
	v_add_u32_e32 v5, v2, v184
	v_add_u32_e32 v6, v2, v185
	v_add_u32_e32 v7, v2, v186
	ds_read_b128 v[210:213], v4
	ds_read_b128 v[214:217], v5
	ds_read_b128 v[218:221], v6
	ds_read_b128 v[222:225], v7
	v_add_u32_e32 v8, v2, v187
	v_add_u32_e32 v9, v2, v188
	v_add_u32_e32 v10, v2, v189
	v_add_u32_e32 v11, v2, v190
	ds_read_b128 v[226:229], v8
	ds_read_b128 v[230:233], v9
	ds_read_b128 v[234:237], v10
	ds_read_b128 v[238:241], v11
	s_cmp_eq_u32 s92, s4
	s_cselect_b64 s[0:1], -1, 0
	s_cmp_eq_u32 s47, s4
	s_cselect_b64 s[66:67], -1, 0
	s_or_b64 s[66:67], s[0:1], s[66:67]
	s_mov_b64 s[0:1], -1
	s_and_b64 vcc, exec, s[66:67]
	v_add_u32_e32 v242, s46, v180
	v_add_u32_e32 v243, s46, v167
	v_add_u32_e32 v244, s46, v191
	v_add_u32_e32 v245, s46, v192
	v_add_u32_e32 v246, s46, v193
	v_add_u32_e32 v247, s46, v194
	v_add_u32_e32 v248, s46, v195
	v_add_u32_e32 v249, s46, v196
	s_waitcnt lgkmcnt(7)
	v_mfma_f32_32x32x16_bf16 v[82:97], v[210:213], v[98:101], 0
	s_waitcnt lgkmcnt(6)
	v_mfma_f32_32x32x16_bf16 v[82:97], v[214:217], v[102:105], v[82:97]
	s_waitcnt lgkmcnt(5)
	v_mfma_f32_32x32x16_bf16 v[82:97], v[218:221], v[106:109], v[82:97]
	s_waitcnt lgkmcnt(4)
	v_mfma_f32_32x32x16_bf16 v[82:97], v[222:225], v[110:113], v[82:97]
	s_waitcnt lgkmcnt(3)
	v_mfma_f32_32x32x16_bf16 v[82:97], v[226:229], v[114:117], v[82:97]
	s_waitcnt lgkmcnt(2)
	v_mfma_f32_32x32x16_bf16 v[82:97], v[230:233], v[118:121], v[82:97]
	s_waitcnt lgkmcnt(1)
	v_mfma_f32_32x32x16_bf16 v[82:97], v[234:237], v[122:125], v[82:97]
	s_waitcnt lgkmcnt(0)
	v_mfma_f32_32x32x16_bf16 v[82:97], v[238:241], v[126:129], v[82:97]
	ds_read_b64_tr_b16 v[210:211], v242 offset:8192
	ds_read_b64_tr_b16 v[212:213], v243 offset:9216
	ds_read_b64_tr_b16 v[214:215], v244 offset:8192
	ds_read_b64_tr_b16 v[216:217], v245 offset:8192
	ds_read_b64_tr_b16 v[218:219], v246 offset:8192
	ds_read_b64_tr_b16 v[220:221], v247 offset:8192
	ds_read_b64_tr_b16 v[222:223], v248 offset:8192
	ds_read_b64_tr_b16 v[224:225], v249 offset:8192
	s_nop 3
	s_cbranch_vccnz .LBB0_407
	v_max3_f32 v2, v82, s80, v83
	v_max3_f32 v2, v2, v84, v85
	v_max3_f32 v2, v2, v86, v87
	v_max3_f32 v2, v2, v88, v89
	v_max3_f32 v2, v2, v90, v91
	v_max3_f32 v2, v2, v92, v93
	v_max3_f32 v2, v2, v94, v95
	v_max3_f32 v2, v2, v96, v97
	s_mov_b64 s[0:1], 0
